# latent differential-attention loop: K / V^T LDS fragments read ahead into spare registers with counted lgkmcnt waits (was one fragment, full wait, one MFMA)
# speedup vs baseline: 1.0624x; 1.0054x over previous
; DI unsigned pack2(float a, float b) { f2 v = {a, b}; bf2 r = __builtin_convertvector(v, bf2); return __builtin_bit_cast(unsigned, r); }
; DI f32x16 mfma32(bf8 a, bf8 b, f32x16 c) { return __builtin_amdgcn_mfma_f32_32x32x16_bf16(a, b, c, 0, 0, 0); }
; DI float ex2(float x) { return __builtin_amdgcn_exp2f(x); }
; template <int DV, int MODE>
; DI void attn_item(const AttnArgs& a, char* smem) {
;     ...
;       float ps0 = 0.f, ps1 = 0.f;
; #pragma unroll
;       for (int kb = 0; kb < 2; ++kb)
; #pragma unroll
;         for (int i = 0; i < 16; i += 2) {
;           f32x2n v = {s[kb][i], s[kb][i + 1]};
;           v = v * f32x2n{SC, SC} - f32x2n{mn, mn};
;           const float p0 = ex2(v.x), p1 = ex2(v.y);
;           s[kb][i] = p0; s[kb][i + 1] = p1;
;           ps0 += p0; ps1 += p1;
;         }
;       if (resc) {
;         const float alpha = ex2(m - mn);
;         m = mn;
;         lsum *= alpha;
; #pragma unroll
;         for (int d = 0; d < NDV; ++d)
; #pragma unroll
;           for (int i = 0; i < 16; ++i) O[d][i] *= alpha;
;       }
;       lsum += ps0 + ps1;
; #pragma unroll
;       for (int kb = 0; kb < 2; ++kb)
; #pragma unroll
;         for (int s2 = 0; s2 < 2; ++s2) {
;           u32x4 pk;
;           pk.x = pack2(s[kb][s2 * 8 + 0], s[kb][s2 * 8 + 1]);
;           pk.y = pack2(s[kb][s2 * 8 + 2], s[kb][s2 * 8 + 3]);
;           pk.z = pack2(s[kb][s2 * 8 + 4], s[kb][s2 * 8 + 5]);
;           pk.w = pack2(s[kb][s2 * 8 + 6], s[kb][s2 * 8 + 7]);
;           const bf8 pf = __builtin_bit_cast(bf8, pk);
; #pragma unroll
;           for (int d = 0; d < NDV; ++d) {
;             const u16* vp = Vs + (d * 32 + r) * 72 + kb * 32 + s2 * 16 + 4 * h;
;             u32x4 vv;
;             const u32x2 lo = *(const u32x2*)(vp);
;             const u32x2 hi = *(const u32x2*)(vp + 8);
;             vv.x = lo.x; vv.y = lo.y; vv.z = hi.x; vv.w = hi.y;
;             O[d] = mfma32(__builtin_bit_cast(bf8, vv), pf, O[d]);
;           }
;         }
.LBB0_553:
	v_pk_fma_f32 v[82:83], v[82:83], s[24:25], v[148:149] op_sel_hi:[1,0,0] neg_lo:[0,0,1] neg_hi:[0,0,1]
	v_pk_fma_f32 v[66:67], v[66:67], s[24:25], v[148:149] op_sel_hi:[1,0,0] neg_lo:[0,0,1] neg_hi:[0,0,1]
	v_exp_f32_e32 v156, v82
	v_exp_f32_e32 v157, v83
	v_pk_fma_f32 v[82:83], v[84:85], s[24:25], v[148:149] op_sel_hi:[1,0,0] neg_lo:[0,0,1] neg_hi:[0,0,1]
	s_add_i32 s3, s3, 1
	v_exp_f32_e32 v84, v82
	v_exp_f32_e32 v85, v83
	v_pk_fma_f32 v[82:83], v[86:87], s[24:25], v[148:149] op_sel_hi:[1,0,0] neg_lo:[0,0,1] neg_hi:[0,0,1]
	v_add_f32_e32 v158, 0, v156
	v_exp_f32_e32 v86, v82
	v_exp_f32_e32 v87, v83
	v_pk_fma_f32 v[82:83], v[88:89], s[24:25], v[148:149] op_sel_hi:[1,0,0] neg_lo:[0,0,1] neg_hi:[0,0,1]
	v_add_f32_e32 v159, 0, v157
	v_exp_f32_e32 v88, v82
	v_exp_f32_e32 v89, v83
	v_pk_fma_f32 v[82:83], v[90:91], s[24:25], v[148:149] op_sel_hi:[1,0,0] neg_lo:[0,0,1] neg_hi:[0,0,1]
	v_add_f32_e32 v158, v84, v158
	v_exp_f32_e32 v90, v82
	v_exp_f32_e32 v91, v83
	v_pk_fma_f32 v[82:83], v[92:93], s[24:25], v[148:149] op_sel_hi:[1,0,0] neg_lo:[0,0,1] neg_hi:[0,0,1]
	v_add_f32_e32 v159, v85, v159
	v_exp_f32_e32 v92, v82
	v_exp_f32_e32 v93, v83
	v_pk_fma_f32 v[82:83], v[94:95], s[24:25], v[148:149] op_sel_hi:[1,0,0] neg_lo:[0,0,1] neg_hi:[0,0,1]
	v_add_f32_e32 v158, v86, v158
	v_add_f32_e32 v159, v87, v159
	v_exp_f32_e32 v94, v82
	v_exp_f32_e32 v95, v83
	v_pk_fma_f32 v[82:83], v[96:97], s[24:25], v[148:149] op_sel_hi:[1,0,0] neg_lo:[0,0,1] neg_hi:[0,0,1]
	v_add_f32_e32 v158, v88, v158
	v_add_f32_e32 v159, v89, v159
	v_exp_f32_e32 v96, v82
	v_exp_f32_e32 v97, v83
	v_add_f32_e32 v158, v90, v158
	v_add_f32_e32 v159, v91, v159
	v_add_f32_e32 v158, v92, v158
	v_add_f32_e32 v159, v93, v159
	v_add_f32_e32 v158, v94, v158
	v_add_f32_e32 v159, v95, v159
	v_add_f32_e32 v82, v96, v158
	v_add_f32_e32 v83, v97, v159
	v_exp_f32_e32 v158, v66
	v_exp_f32_e32 v159, v67
	v_pk_fma_f32 v[66:67], v[68:69], s[24:25], v[148:149] op_sel_hi:[1,0,0] neg_lo:[0,0,1] neg_hi:[0,0,1]
	s_add_i32 s0, s0, 64
	v_exp_f32_e32 v160, v66
	v_exp_f32_e32 v161, v67
	v_pk_fma_f32 v[66:67], v[70:71], s[24:25], v[148:149] op_sel_hi:[1,0,0] neg_lo:[0,0,1] neg_hi:[0,0,1]
	v_add_f32_e32 v82, v158, v82
	v_exp_f32_e32 v164, v66
	v_exp_f32_e32 v165, v67
	v_pk_fma_f32 v[66:67], v[72:73], s[24:25], v[148:149] op_sel_hi:[1,0,0] neg_lo:[0,0,1] neg_hi:[0,0,1]
	v_add_f32_e32 v83, v159, v83
	v_exp_f32_e32 v166, v66
	v_exp_f32_e32 v167, v67
	v_pk_fma_f32 v[66:67], v[74:75], s[24:25], v[148:149] op_sel_hi:[1,0,0] neg_lo:[0,0,1] neg_hi:[0,0,1]
	v_add_f32_e32 v68, v160, v82
	v_exp_f32_e32 v71, v66
	v_exp_f32_e32 v72, v67
	v_pk_fma_f32 v[66:67], v[76:77], s[24:25], v[148:149] op_sel_hi:[1,0,0] neg_lo:[0,0,1] neg_hi:[0,0,1]
	v_add_f32_e32 v69, v161, v83
	v_exp_f32_e32 v73, v66
	v_exp_f32_e32 v74, v67
	v_pk_fma_f32 v[66:67], v[78:79], s[24:25], v[148:149] op_sel_hi:[1,0,0] neg_lo:[0,0,1] neg_hi:[0,0,1]
	v_add_f32_e32 v68, v164, v68
	v_add_f32_e32 v69, v165, v69
	v_exp_f32_e32 v75, v66
	v_exp_f32_e32 v76, v67
	v_pk_fma_f32 v[66:67], v[80:81], s[24:25], v[148:149] op_sel_hi:[1,0,0] neg_lo:[0,0,1] neg_hi:[0,0,1]
	v_add_f32_e32 v68, v166, v68
	v_add_f32_e32 v69, v167, v69
	v_exp_f32_e32 v77, v66
	v_exp_f32_e32 v78, v67
	v_add_f32_e32 v68, v71, v68
	v_add_f32_e32 v69, v72, v69
	v_add_f32_e32 v68, v73, v68
	v_add_f32_e32 v69, v74, v69
	v_add_f32_e32 v68, v75, v68
	v_add_f32_e32 v69, v76, v69
	v_add_f32_e32 v66, v77, v68
	v_add_f32_e32 v67, v78, v69
	v_add_u32_e32 v79, 0x4800, v154
	v_add_u32_e32 v250, 0x5800, v154
	v_add_u32_e32 v251, 0x6800, v154
	v_add_u32_e32 v252, 0x7800, v154
	v_add_f32_e32 v70, v66, v67
	v_cvt_pk_bf16_f32 v67, v84, v85
	v_cvt_pk_bf16_f32 v68, v86, v87
	ds_read2_b64 v[80:83], v79 offset1:2
	ds_read2_b64 v[84:87], v79 offset0:4 offset1:6
	ds_read2_b64 v[238:241], v250 offset0:64 offset1:66
	ds_read2_b64 v[242:245], v251 offset0:128 offset1:130
	ds_read2_b64 v[246:249], v252 offset0:192 offset1:194
	v_cvt_pk_bf16_f32 v66, v156, v157
	v_cvt_pk_bf16_f32 v69, v88, v89
	v_add_f32_e32 v152, v70, v152
	s_cmp_eq_u32 s3, 36
	s_waitcnt lgkmcnt(4)
	v_mfma_f32_32x32x16_bf16 v[50:65], v[80:83], v[66:69], v[50:65]
	ds_read2_b64 v[80:83], v250 offset0:68 offset1:70
	s_waitcnt lgkmcnt(3)
	v_mfma_f32_32x32x16_bf16 v[34:49], v[238:241], v[66:69], v[34:49]
	ds_read2_b64 v[238:241], v251 offset0:132 offset1:134
	s_waitcnt lgkmcnt(3)
	v_mfma_f32_32x32x16_bf16 v[18:33], v[242:245], v[66:69], v[18:33]
	ds_read2_b64 v[242:245], v252 offset0:196 offset1:198
	s_waitcnt lgkmcnt(3)
	v_mfma_f32_32x32x16_bf16 v[2:17], v[246:249], v[66:69], v[2:17]
	ds_read2_b64 v[246:249], v79 offset0:8 offset1:10
	v_cvt_pk_bf16_f32 v66, v90, v91
	v_cvt_pk_bf16_f32 v67, v92, v93
	v_cvt_pk_bf16_f32 v68, v94, v95
	v_cvt_pk_bf16_f32 v69, v96, v97
	s_waitcnt lgkmcnt(3)
	s_nop 0
	v_mfma_f32_32x32x16_bf16 v[34:49], v[80:83], v[66:69], v[34:49]
	ds_read2_b64 v[80:83], v250 offset0:72 offset1:74
	s_waitcnt lgkmcnt(3)
	v_mfma_f32_32x32x16_bf16 v[18:33], v[238:241], v[66:69], v[18:33]
	ds_read2_b64 v[238:241], v251 offset0:136 offset1:138
	s_waitcnt lgkmcnt(3)
	v_mfma_f32_32x32x16_bf16 v[2:17], v[242:245], v[66:69], v[2:17]
	ds_read2_b64 v[242:245], v252 offset0:200 offset1:202
	v_mfma_f32_32x32x16_bf16 v[50:65], v[84:87], v[66:69], v[50:65]
	v_cvt_pk_bf16_f32 v66, v158, v159
	v_cvt_pk_bf16_f32 v67, v160, v161
	v_cvt_pk_bf16_f32 v68, v164, v165
	v_cvt_pk_bf16_f32 v69, v166, v167
	s_waitcnt lgkmcnt(3)
	s_nop 0
	v_mfma_f32_32x32x16_bf16 v[50:65], v[246:249], v[66:69], v[50:65]
	ds_read2_b64 v[246:249], v79 offset0:12 offset1:14
	s_waitcnt lgkmcnt(3)
	v_mfma_f32_32x32x16_bf16 v[34:49], v[80:83], v[66:69], v[34:49]
	ds_read2_b64 v[80:83], v250 offset0:76 offset1:78
	s_waitcnt lgkmcnt(3)
	v_mfma_f32_32x32x16_bf16 v[18:33], v[238:241], v[66:69], v[18:33]
	ds_read2_b64 v[238:241], v251 offset0:140 offset1:142
	s_waitcnt lgkmcnt(3)
	v_mfma_f32_32x32x16_bf16 v[2:17], v[242:245], v[66:69], v[2:17]
	ds_read2_b64 v[242:245], v252 offset0:204 offset1:206
	v_cvt_pk_bf16_f32 v66, v71, v72
	v_cvt_pk_bf16_f32 v67, v73, v74
	v_cvt_pk_bf16_f32 v68, v75, v76
	v_cvt_pk_bf16_f32 v69, v77, v78
	s_waitcnt lgkmcnt(3)
	s_nop 0
	v_mfma_f32_32x32x16_bf16 v[50:65], v[246:249], v[66:69], v[50:65]
	s_waitcnt lgkmcnt(2)
	v_mfma_f32_32x32x16_bf16 v[34:49], v[80:83], v[66:69], v[34:49]
	s_waitcnt lgkmcnt(1)
	v_mfma_f32_32x32x16_bf16 v[18:33], v[238:241], v[66:69], v[18:33]
	s_waitcnt lgkmcnt(0)
	v_mfma_f32_32x32x16_bf16 v[2:17], v[242:245], v[66:69], v[2:17]
	s_cbranch_scc1 .LBB0_558

; DI int crow(int i, int h) { return (i & 3) + 8 * (i >> 2) + 4 * h; }
; DI f32x16 mfma32(bf8 a, bf8 b, f32x16 c) { return __builtin_amdgcn_mfma_f32_32x32x16_bf16(a, b, c, 0, 0, 0); }
; DI float shx(float v, int lane, int mask) { return __int_as_float(__builtin_amdgcn_ds_bpermute((lane ^ mask) << 2, __float_as_int(v))); }
; template <int DV, int MODE>
; DI void attn_item(const AttnArgs& a, char* smem) {
;     ...
;       f32x16 s[2];
; #pragma unroll
;       for (int kb = 0; kb < 2; ++kb) {
; #pragma unroll
;         for (int i = 0; i < 16; ++i) s[kb][i] = 0.f;
; #pragma unroll
;         for (int ks = 0; ks < 4; ++ks) {
;           const bf8 kf = *(const bf8*)(Ks + (kb * 32 + r) * 72 + ks * 16 + h * 8);
;           s[kb] = mfma32(kf, qf[ks], s[kb]);
;         }
;       }
;       constexpr float SC = 0.125f * LOG2E;
;       float mx = -INFINITY;
;       if (local) {
; #pragma unroll
;         for (int kb = 0; kb < 2; ++kb)
; #pragma unroll
;           for (int i = 0; i < 16; ++i) {
;             const int kc = kb * 32 + crow(i, h);
;             const bool ok = (kc >= cs) && (kc < cs + 16);
;             const int dc = kc - qc + 15;
;             const int dr = kr - rq + 7;
;             const float bias = rpbS[dr * 32 + (ok ? dc : 0)];
;             const float v = ok ? (s[kb][i] + bias * (1.f / SC)) : -INFINITY;
;             s[kb][i] = v;
;             mx = fmaxf(mx, v);
;           }
;       } else {
; #pragma unroll
;         for (int kb = 0; kb < 2; ++kb)
; #pragma unroll
;           for (int i = 0; i < 16; i += 2) mx = fmaxf(fmaxf(mx, s[kb][i]), s[kb][i + 1]);
;       }
;       mx = fmaxf(mx, shx(mx, lane, 32)) * SC;
.LBB0_556:
	ds_read_b128 v[66:69], v153
	ds_read_b128 v[70:73], v153 offset:32
	ds_read_b128 v[74:77], v153 offset:64
	ds_read_b128 v[78:81], v153 offset:96
	ds_read_b128 v[156:159], v153 offset:4608
	ds_read_b128 v[238:241], v153 offset:4640
	ds_read_b128 v[242:245], v153 offset:4672
	ds_read_b128 v[246:249], v153 offset:4704
	s_waitcnt lgkmcnt(7)
	v_mfma_f32_32x32x16_bf16 v[82:97], v[66:69], v[98:101], 0
	s_waitcnt lgkmcnt(6)
	v_mfma_f32_32x32x16_bf16 v[82:97], v[70:73], v[102:105], v[82:97]
	s_waitcnt lgkmcnt(5)
	v_mfma_f32_32x32x16_bf16 v[82:97], v[74:77], v[106:109], v[82:97]
	s_waitcnt lgkmcnt(4)
	v_mfma_f32_32x32x16_bf16 v[82:97], v[78:81], v[110:113], v[82:97]
	s_waitcnt lgkmcnt(3)
	v_mfma_f32_32x32x16_bf16 v[66:81], v[156:159], v[98:101], 0
	s_waitcnt lgkmcnt(2)
	v_mfma_f32_32x32x16_bf16 v[66:81], v[238:241], v[102:105], v[66:81]
	s_waitcnt lgkmcnt(1)
	v_mfma_f32_32x32x16_bf16 v[66:81], v[242:245], v[106:109], v[66:81]
	s_waitcnt lgkmcnt(0)
	v_mfma_f32_32x32x16_bf16 v[66:81], v[246:249], v[110:113], v[66:81]
	s_nop 3
	v_max3_f32 v148, v82, s33, v83
	v_max3_f32 v148, v148, v84, v85
	v_max3_f32 v148, v148, v86, v87
	v_max3_f32 v148, v148, v88, v89
	v_max3_f32 v148, v148, v90, v91
	v_max3_f32 v148, v148, v92, v93
	v_max3_f32 v148, v148, v94, v95
	v_max3_f32 v148, v148, v96, v97
	v_max3_f32 v148, v148, v66, v67
	v_max3_f32 v148, v148, v68, v69
	v_max3_f32 v148, v148, v70, v71
	v_max3_f32 v148, v148, v72, v73
	v_max3_f32 v148, v148, v74, v75
	v_max3_f32 v148, v148, v76, v77
	v_max3_f32 v148, v148, v78, v79
	v_max3_f32 v148, v148, v80, v81
	v_mul_f32_e32 v156, 0x3e38aa3b, v148
	v_sub_f32_e32 v156, v156, v155
	v_cmp_lt_f32_e32 vcc, 8.0, v156
	s_cbranch_vccnz .Llz_8
	v_mov_b32_e32 v148, v155
	s_branch .LBB0_553
